# DSA attend: softmax stores 0 for slots past nsel; P.V loop drops per-group v_cmp/clamp/cndmask (plain moves) and shares one LDS address for the 8 probability reads
# speedup vs baseline: 1.0028x; 1.0028x over previous
.Ldsa_sm_loop:
	ds_read_b32 v208, v3
	ds_read_b32 v209, v3 offset:256
	ds_read_b32 v210, v3 offset:512
	ds_read_b32 v211, v3 offset:768
	ds_read_b32 v212, v3 offset:1024
	ds_read_b32 v213, v3 offset:1280
	ds_read_b32 v214, v3 offset:1536
	ds_read_b32 v215, v3 offset:1792
	s_waitcnt lgkmcnt(0)
	v_sub_f32_e32 v208, v208, v2
	v_sub_f32_e32 v209, v209, v2
	v_sub_f32_e32 v210, v210, v2
	v_sub_f32_e32 v211, v211, v2
	v_sub_f32_e32 v212, v212, v2
	v_sub_f32_e32 v213, v213, v2
	v_sub_f32_e32 v214, v214, v2
	v_sub_f32_e32 v215, v215, v2
	v_mul_f32_e32 v208, 0x3fb8aa3b, v208
	v_mul_f32_e32 v209, 0x3fb8aa3b, v209
	v_mul_f32_e32 v210, 0x3fb8aa3b, v210
	v_mul_f32_e32 v211, 0x3fb8aa3b, v211
	v_mul_f32_e32 v212, 0x3fb8aa3b, v212
	v_mul_f32_e32 v213, 0x3fb8aa3b, v213
	v_mul_f32_e32 v214, 0x3fb8aa3b, v214
	v_mul_f32_e32 v215, 0x3fb8aa3b, v215
	v_exp_f32_e32 v208, v208
	v_exp_f32_e32 v209, v209
	v_exp_f32_e32 v210, v210
	v_exp_f32_e32 v211, v211
	v_exp_f32_e32 v212, v212
	v_exp_f32_e32 v213, v213
	v_exp_f32_e32 v214, v214
	v_exp_f32_e32 v215, v215
	v_add_u32_e32 v217, 8, v4
	v_add_u32_e32 v218, 16, v4
	v_add_u32_e32 v219, 24, v4
	v_add_u32_e32 v220, 32, v4
	v_add_u32_e32 v221, 40, v4
	v_add_u32_e32 v222, 48, v4
	v_add_u32_e32 v223, 56, v4
	v_cmp_ge_u32_e32 vcc, s50, v4
	s_nop 1
	v_cndmask_b32_e32 v208, 0, v208, vcc
	v_add_f32_e32 v15, v15, v208
	v_cmp_ge_u32_e32 vcc, s50, v217
	s_nop 1
	v_cndmask_b32_e32 v209, 0, v209, vcc
	v_add_f32_e32 v15, v15, v209
	v_cmp_ge_u32_e32 vcc, s50, v218
	s_nop 1
	v_cndmask_b32_e32 v210, 0, v210, vcc
	v_add_f32_e32 v15, v15, v210
	v_cmp_ge_u32_e32 vcc, s50, v219
	s_nop 1
	v_cndmask_b32_e32 v211, 0, v211, vcc
	v_add_f32_e32 v15, v15, v211
	v_cmp_ge_u32_e32 vcc, s50, v220
	s_nop 1
	v_cndmask_b32_e32 v212, 0, v212, vcc
	v_add_f32_e32 v15, v15, v212
	v_cmp_ge_u32_e32 vcc, s50, v221
	s_nop 1
	v_cndmask_b32_e32 v213, 0, v213, vcc
	v_add_f32_e32 v15, v15, v213
	v_cmp_ge_u32_e32 vcc, s50, v222
	s_nop 1
	v_cndmask_b32_e32 v214, 0, v214, vcc
	v_add_f32_e32 v15, v15, v214
	v_cmp_ge_u32_e32 vcc, s50, v223
	s_nop 1
	v_cndmask_b32_e32 v215, 0, v215, vcc
	v_add_f32_e32 v15, v15, v215
	ds_write_b32 v3, v208
	ds_write_b32 v3, v209 offset:256
	ds_write_b32 v3, v210 offset:512
	ds_write_b32 v3, v211 offset:768
	ds_write_b32 v3, v212 offset:1024
	ds_write_b32 v3, v213 offset:1280
	ds_write_b32 v3, v214 offset:1536
	ds_write_b32 v3, v215 offset:1792
	v_add_u32_e32 v4, 64, v4
	v_add_u32_e32 v3, 0x800, v3
	s_sub_u32 s42, s42, 1
	s_cmp_lg_u32 s42, 0
	s_cbranch_scc1 .Ldsa_sm_loop

.LBB0_275:
	v_lshl_add_u32 v240, v103, 5, v202
	ds_read_b128 v[208:211], v240
	ds_read_b128 v[212:215], v240 offset:128
	ds_read_b128 v[216:219], v240 offset:256
	ds_read_b128 v[220:223], v240 offset:384
	ds_read_b128 v[224:227], v240 offset:512
	ds_read_b128 v[228:231], v240 offset:640
	ds_read_b128 v[232:235], v240 offset:768
	ds_read_b128 v[236:239], v240 offset:896
	v_lshlrev_b32_e32 v114, 16, v62
	v_and_b32_e32 v115, 0xffff0000, v62
	v_lshlrev_b32_e32 v62, 16, v63
	s_waitcnt lgkmcnt(7)
	v_mov_b32_e32 v110, v211
	v_mov_b32_e32 v108, v210
	v_mov_b32_e32 v112, v209
	v_mov_b32_e32 v106, v208
	v_and_b32_e32 v63, 0xffff0000, v63
	v_pk_fma_f32 v[88:89], v[106:107], v[62:63], v[88:89] op_sel_hi:[0,1,1]
	v_pk_fma_f32 v[86:87], v[112:113], v[62:63], v[86:87] op_sel_hi:[0,1,1]
	v_pk_fma_f32 v[84:85], v[108:109], v[62:63], v[84:85] op_sel_hi:[0,1,1]
	v_pk_fma_f32 v[82:83], v[110:111], v[62:63], v[82:83] op_sel_hi:[0,1,1]
	v_lshlrev_b32_e32 v116, 16, v64
	v_and_b32_e32 v117, 0xffff0000, v64
	v_lshlrev_b32_e32 v64, 16, v65
	v_and_b32_e32 v65, 0xffff0000, v65
	v_pk_fma_f32 v[72:73], v[106:107], v[64:65], v[72:73] op_sel_hi:[0,1,1]
	v_pk_fma_f32 v[70:71], v[112:113], v[64:65], v[70:71] op_sel_hi:[0,1,1]
	v_pk_fma_f32 v[68:69], v[108:109], v[64:65], v[68:69] op_sel_hi:[0,1,1]
	v_pk_fma_f32 v[66:67], v[110:111], v[64:65], v[66:67] op_sel_hi:[0,1,1]
	v_pk_fma_f32 v[92:93], v[106:107], v[114:115], v[92:93] op_sel_hi:[0,1,1]
	v_pk_fma_f32 v[80:81], v[106:107], v[116:117], v[80:81] op_sel_hi:[0,1,1]
	v_pk_fma_f32 v[94:95], v[108:109], v[114:115], v[94:95] op_sel_hi:[0,1,1]
	v_pk_fma_f32 v[74:75], v[108:109], v[116:117], v[74:75] op_sel_hi:[0,1,1]
	v_pk_fma_f32 v[90:91], v[110:111], v[114:115], v[90:91] op_sel_hi:[0,1,1]
	v_pk_fma_f32 v[76:77], v[110:111], v[116:117], v[76:77] op_sel_hi:[0,1,1]
	s_waitcnt lgkmcnt(6)
	v_mov_b32_e32 v106, v215
	v_mov_b32_e32 v64, v214
	v_mov_b32_e32 v108, v213
	v_mov_b32_e32 v62, v212
	v_lshlrev_b32_e32 v110, 16, v58
	v_and_b32_e32 v111, 0xffff0000, v58
	v_lshlrev_b32_e32 v58, 16, v59
	v_and_b32_e32 v59, 0xffff0000, v59
	v_pk_fma_f32 v[88:89], v[62:63], v[58:59], v[88:89] op_sel_hi:[0,1,1]
	v_pk_fma_f32 v[86:87], v[108:109], v[58:59], v[86:87] op_sel_hi:[0,1,1]
	v_pk_fma_f32 v[84:85], v[64:65], v[58:59], v[84:85] op_sel_hi:[0,1,1]
	v_pk_fma_f32 v[82:83], v[106:107], v[58:59], v[82:83] op_sel_hi:[0,1,1]
	v_pk_fma_f32 v[96:97], v[112:113], v[114:115], v[96:97] op_sel_hi:[0,1,1]
	v_pk_fma_f32 v[78:79], v[112:113], v[116:117], v[78:79] op_sel_hi:[0,1,1]
	v_lshlrev_b32_e32 v112, 16, v60
	v_and_b32_e32 v113, 0xffff0000, v60
	v_lshlrev_b32_e32 v60, 16, v61
	v_and_b32_e32 v61, 0xffff0000, v61
	v_pk_fma_f32 v[72:73], v[62:63], v[60:61], v[72:73] op_sel_hi:[0,1,1]
	v_pk_fma_f32 v[70:71], v[108:109], v[60:61], v[70:71] op_sel_hi:[0,1,1]
	v_pk_fma_f32 v[68:69], v[64:65], v[60:61], v[68:69] op_sel_hi:[0,1,1]
	v_pk_fma_f32 v[66:67], v[106:107], v[60:61], v[66:67] op_sel_hi:[0,1,1]
	v_pk_fma_f32 v[80:81], v[62:63], v[112:113], v[80:81] op_sel_hi:[0,1,1]
	v_pk_fma_f32 v[62:63], v[62:63], v[110:111], v[92:93] op_sel_hi:[0,1,1]
	v_pk_fma_f32 v[92:93], v[108:109], v[110:111], v[96:97] op_sel_hi:[0,1,1]
	v_pk_fma_f32 v[74:75], v[64:65], v[112:113], v[74:75] op_sel_hi:[0,1,1]
	v_pk_fma_f32 v[64:65], v[64:65], v[110:111], v[94:95] op_sel_hi:[0,1,1]
	v_pk_fma_f32 v[76:77], v[106:107], v[112:113], v[76:77] op_sel_hi:[0,1,1]
	v_pk_fma_f32 v[90:91], v[106:107], v[110:111], v[90:91] op_sel_hi:[0,1,1]
	s_waitcnt lgkmcnt(5)
	v_mov_b32_e32 v94, v219
	v_mov_b32_e32 v60, v218
	v_mov_b32_e32 v96, v217
	v_mov_b32_e32 v58, v216
	v_lshlrev_b32_e32 v106, 16, v54
	v_and_b32_e32 v107, 0xffff0000, v54
	v_lshlrev_b32_e32 v54, 16, v55
	v_and_b32_e32 v55, 0xffff0000, v55
	v_pk_fma_f32 v[88:89], v[58:59], v[54:55], v[88:89] op_sel_hi:[0,1,1]
	v_pk_fma_f32 v[86:87], v[96:97], v[54:55], v[86:87] op_sel_hi:[0,1,1]
	v_pk_fma_f32 v[84:85], v[60:61], v[54:55], v[84:85] op_sel_hi:[0,1,1]
	v_pk_fma_f32 v[82:83], v[94:95], v[54:55], v[82:83] op_sel_hi:[0,1,1]
	v_pk_fma_f32 v[78:79], v[108:109], v[112:113], v[78:79] op_sel_hi:[0,1,1]
	v_lshlrev_b32_e32 v108, 16, v56
	v_and_b32_e32 v109, 0xffff0000, v56
	v_lshlrev_b32_e32 v56, 16, v57
	v_and_b32_e32 v57, 0xffff0000, v57
	v_pk_fma_f32 v[62:63], v[58:59], v[106:107], v[62:63] op_sel_hi:[0,1,1]
	v_pk_fma_f32 v[80:81], v[58:59], v[108:109], v[80:81] op_sel_hi:[0,1,1]
	v_pk_fma_f32 v[58:59], v[58:59], v[56:57], v[72:73] op_sel_hi:[0,1,1]
	v_pk_fma_f32 v[70:71], v[96:97], v[56:57], v[70:71] op_sel_hi:[0,1,1]
	v_pk_fma_f32 v[64:65], v[60:61], v[106:107], v[64:65] op_sel_hi:[0,1,1]
	v_pk_fma_f32 v[74:75], v[60:61], v[108:109], v[74:75] op_sel_hi:[0,1,1]
	v_pk_fma_f32 v[60:61], v[60:61], v[56:57], v[68:69] op_sel_hi:[0,1,1]
	v_pk_fma_f32 v[66:67], v[94:95], v[56:57], v[66:67] op_sel_hi:[0,1,1]
	v_pk_fma_f32 v[72:73], v[96:97], v[106:107], v[92:93] op_sel_hi:[0,1,1]
	v_pk_fma_f32 v[78:79], v[96:97], v[108:109], v[78:79] op_sel_hi:[0,1,1]
	v_pk_fma_f32 v[68:69], v[94:95], v[106:107], v[90:91] op_sel_hi:[0,1,1]
	v_pk_fma_f32 v[76:77], v[94:95], v[108:109], v[76:77] op_sel_hi:[0,1,1]
	s_waitcnt lgkmcnt(4)
	v_mov_b32_e32 v90, v223
	v_mov_b32_e32 v56, v222
	v_mov_b32_e32 v92, v221
	v_mov_b32_e32 v54, v220
	v_lshlrev_b32_e32 v94, 16, v50
	v_and_b32_e32 v95, 0xffff0000, v50
	v_lshlrev_b32_e32 v50, 16, v51
	v_and_b32_e32 v51, 0xffff0000, v51
	v_lshlrev_b32_e32 v96, 16, v52
	v_and_b32_e32 v97, 0xffff0000, v52
	v_lshlrev_b32_e32 v52, 16, v53
	v_and_b32_e32 v53, 0xffff0000, v53
	v_pk_fma_f32 v[58:59], v[54:55], v[52:53], v[58:59] op_sel_hi:[0,1,1]
	v_pk_fma_f32 v[80:81], v[54:55], v[96:97], v[80:81] op_sel_hi:[0,1,1]
	v_pk_fma_f32 v[88:89], v[54:55], v[50:51], v[88:89] op_sel_hi:[0,1,1]
	v_pk_fma_f32 v[54:55], v[54:55], v[94:95], v[62:63] op_sel_hi:[0,1,1]
	v_pk_fma_f32 v[62:63], v[92:93], v[52:53], v[70:71] op_sel_hi:[0,1,1]
	v_pk_fma_f32 v[70:71], v[92:93], v[96:97], v[78:79] op_sel_hi:[0,1,1]
	v_pk_fma_f32 v[78:79], v[92:93], v[50:51], v[86:87] op_sel_hi:[0,1,1]
	v_pk_fma_f32 v[60:61], v[56:57], v[52:53], v[60:61] op_sel_hi:[0,1,1]
	v_pk_fma_f32 v[74:75], v[56:57], v[96:97], v[74:75] op_sel_hi:[0,1,1]
	v_pk_fma_f32 v[84:85], v[56:57], v[50:51], v[84:85] op_sel_hi:[0,1,1]
	v_pk_fma_f32 v[56:57], v[56:57], v[94:95], v[64:65] op_sel_hi:[0,1,1]
	v_pk_fma_f32 v[64:65], v[90:91], v[52:53], v[66:67] op_sel_hi:[0,1,1]
	v_pk_fma_f32 v[66:67], v[90:91], v[96:97], v[76:77] op_sel_hi:[0,1,1]
	v_pk_fma_f32 v[76:77], v[90:91], v[50:51], v[82:83] op_sel_hi:[0,1,1]
	v_pk_fma_f32 v[72:73], v[92:93], v[94:95], v[72:73] op_sel_hi:[0,1,1]
	v_pk_fma_f32 v[68:69], v[90:91], v[94:95], v[68:69] op_sel_hi:[0,1,1]
	v_lshlrev_b32_e32 v90, 16, v46
	v_and_b32_e32 v91, 0xffff0000, v46
	s_waitcnt lgkmcnt(3)
	v_mov_b32_e32 v82, v227
	v_mov_b32_e32 v52, v226
	v_mov_b32_e32 v86, v225
	v_mov_b32_e32 v50, v224
	v_lshlrev_b32_e32 v46, 16, v47
	v_and_b32_e32 v47, 0xffff0000, v47
	v_lshlrev_b32_e32 v92, 16, v48
	v_and_b32_e32 v93, 0xffff0000, v48
	v_lshlrev_b32_e32 v48, 16, v49
	v_and_b32_e32 v49, 0xffff0000, v49
	v_pk_fma_f32 v[54:55], v[50:51], v[90:91], v[54:55] op_sel_hi:[0,1,1]
	v_pk_fma_f32 v[88:89], v[50:51], v[46:47], v[88:89] op_sel_hi:[0,1,1]
	v_pk_fma_f32 v[80:81], v[50:51], v[92:93], v[80:81] op_sel_hi:[0,1,1]
	v_pk_fma_f32 v[50:51], v[50:51], v[48:49], v[58:59] op_sel_hi:[0,1,1]
	v_pk_fma_f32 v[58:59], v[86:87], v[90:91], v[72:73] op_sel_hi:[0,1,1]
	v_pk_fma_f32 v[72:73], v[86:87], v[46:47], v[78:79] op_sel_hi:[0,1,1]
	v_pk_fma_f32 v[56:57], v[52:53], v[90:91], v[56:57] op_sel_hi:[0,1,1]
	v_pk_fma_f32 v[78:79], v[52:53], v[46:47], v[84:85] op_sel_hi:[0,1,1]
	v_pk_fma_f32 v[74:75], v[52:53], v[92:93], v[74:75] op_sel_hi:[0,1,1]
	v_pk_fma_f32 v[52:53], v[52:53], v[48:49], v[60:61] op_sel_hi:[0,1,1]
	v_pk_fma_f32 v[60:61], v[82:83], v[90:91], v[68:69] op_sel_hi:[0,1,1]
	v_pk_fma_f32 v[68:69], v[82:83], v[46:47], v[76:77] op_sel_hi:[0,1,1]
	v_pk_fma_f32 v[62:63], v[86:87], v[48:49], v[62:63] op_sel_hi:[0,1,1]
	v_pk_fma_f32 v[64:65], v[82:83], v[48:49], v[64:65] op_sel_hi:[0,1,1]
	v_pk_fma_f32 v[70:71], v[86:87], v[92:93], v[70:71] op_sel_hi:[0,1,1]
	v_pk_fma_f32 v[66:67], v[82:83], v[92:93], v[66:67] op_sel_hi:[0,1,1]
	v_lshlrev_b32_e32 v84, 16, v10
	v_and_b32_e32 v85, 0xffff0000, v10
	s_waitcnt lgkmcnt(2)
	v_mov_b32_e32 v76, v231
	v_mov_b32_e32 v48, v230
	v_mov_b32_e32 v82, v229
	v_mov_b32_e32 v46, v228
	v_lshlrev_b32_e32 v10, 16, v11
	v_and_b32_e32 v11, 0xffff0000, v11
	v_lshlrev_b32_e32 v86, 16, v12
	v_and_b32_e32 v87, 0xffff0000, v12
	v_lshlrev_b32_e32 v12, 16, v13
	v_and_b32_e32 v13, 0xffff0000, v13
	v_pk_fma_f32 v[50:51], v[46:47], v[12:13], v[50:51] op_sel_hi:[0,1,1]
	v_pk_fma_f32 v[80:81], v[46:47], v[86:87], v[80:81] op_sel_hi:[0,1,1]
	v_pk_fma_f32 v[88:89], v[46:47], v[10:11], v[88:89] op_sel_hi:[0,1,1]
	v_pk_fma_f32 v[46:47], v[46:47], v[84:85], v[54:55] op_sel_hi:[0,1,1]
	v_pk_fma_f32 v[54:55], v[82:83], v[12:13], v[62:63] op_sel_hi:[0,1,1]
	v_pk_fma_f32 v[62:63], v[82:83], v[86:87], v[70:71] op_sel_hi:[0,1,1]
	v_pk_fma_f32 v[70:71], v[82:83], v[10:11], v[72:73] op_sel_hi:[0,1,1]
	v_pk_fma_f32 v[52:53], v[48:49], v[12:13], v[52:53] op_sel_hi:[0,1,1]
	v_pk_fma_f32 v[72:73], v[48:49], v[86:87], v[74:75] op_sel_hi:[0,1,1]
	v_pk_fma_f32 v[74:75], v[48:49], v[10:11], v[78:79] op_sel_hi:[0,1,1]
	v_pk_fma_f32 v[48:49], v[48:49], v[84:85], v[56:57] op_sel_hi:[0,1,1]
	v_pk_fma_f32 v[56:57], v[76:77], v[12:13], v[64:65] op_sel_hi:[0,1,1]
	v_pk_fma_f32 v[64:65], v[76:77], v[86:87], v[66:67] op_sel_hi:[0,1,1]
	v_pk_fma_f32 v[66:67], v[76:77], v[10:11], v[68:69] op_sel_hi:[0,1,1]
	v_pk_fma_f32 v[58:59], v[82:83], v[84:85], v[58:59] op_sel_hi:[0,1,1]
	v_pk_fma_f32 v[60:61], v[76:77], v[84:85], v[60:61] op_sel_hi:[0,1,1]
	v_lshlrev_b32_e32 v78, 16, v6
	v_and_b32_e32 v79, 0xffff0000, v6
	s_waitcnt lgkmcnt(1)
	v_mov_b32_e32 v68, v235
	v_mov_b32_e32 v12, v234
	v_mov_b32_e32 v76, v233
	v_mov_b32_e32 v10, v232
	v_lshlrev_b32_e32 v6, 16, v7
	v_and_b32_e32 v7, 0xffff0000, v7
	v_lshlrev_b32_e32 v82, 16, v8
	v_and_b32_e32 v83, 0xffff0000, v8
	v_lshlrev_b32_e32 v8, 16, v9
	v_and_b32_e32 v9, 0xffff0000, v9
	v_pk_fma_f32 v[46:47], v[10:11], v[78:79], v[46:47] op_sel_hi:[0,1,1]
	v_pk_fma_f32 v[84:85], v[10:11], v[6:7], v[88:89] op_sel_hi:[0,1,1]
	v_pk_fma_f32 v[80:81], v[10:11], v[82:83], v[80:81] op_sel_hi:[0,1,1]
	v_pk_fma_f32 v[10:11], v[10:11], v[8:9], v[50:51] op_sel_hi:[0,1,1]
	v_pk_fma_f32 v[50:51], v[76:77], v[78:79], v[58:59] op_sel_hi:[0,1,1]
	v_pk_fma_f32 v[58:59], v[76:77], v[6:7], v[70:71] op_sel_hi:[0,1,1]
	v_pk_fma_f32 v[62:63], v[76:77], v[82:83], v[62:63] op_sel_hi:[0,1,1]
	v_pk_fma_f32 v[54:55], v[76:77], v[8:9], v[54:55] op_sel_hi:[0,1,1]
	v_pk_fma_f32 v[48:49], v[12:13], v[78:79], v[48:49] op_sel_hi:[0,1,1]
	v_pk_fma_f32 v[76:77], v[12:13], v[6:7], v[74:75] op_sel_hi:[0,1,1]
	v_pk_fma_f32 v[74:75], v[12:13], v[82:83], v[72:73] op_sel_hi:[0,1,1]
	v_pk_fma_f32 v[12:13], v[12:13], v[8:9], v[52:53] op_sel_hi:[0,1,1]
	v_pk_fma_f32 v[52:53], v[68:69], v[78:79], v[60:61] op_sel_hi:[0,1,1]
	v_pk_fma_f32 v[60:61], v[68:69], v[6:7], v[66:67] op_sel_hi:[0,1,1]
	v_pk_fma_f32 v[56:57], v[68:69], v[8:9], v[56:57] op_sel_hi:[0,1,1]
	v_pk_fma_f32 v[64:65], v[68:69], v[82:83], v[64:65] op_sel_hi:[0,1,1]
	v_lshlrev_b32_e32 v106, 16, v2
	v_and_b32_e32 v107, 0xffff0000, v2
	v_lshlrev_b32_e32 v2, 16, v3
	s_waitcnt lgkmcnt(0)
	v_mov_b32_e32 v90, v239
	v_mov_b32_e32 v8, v238
	v_mov_b32_e32 v66, v237
	v_mov_b32_e32 v6, v236
	v_and_b32_e32 v3, 0xffff0000, v3
	v_lshlrev_b32_e32 v82, 16, v4
	v_and_b32_e32 v83, 0xffff0000, v4
	v_lshlrev_b32_e32 v4, 16, v5
	v_and_b32_e32 v5, 0xffff0000, v5
	v_pk_fma_f32 v[72:73], v[6:7], v[4:5], v[10:11] op_sel_hi:[0,1,1]
	v_pk_fma_f32 v[80:81], v[6:7], v[82:83], v[80:81] op_sel_hi:[0,1,1]
	v_pk_fma_f32 v[88:89], v[6:7], v[2:3], v[84:85] op_sel_hi:[0,1,1]
	v_pk_fma_f32 v[92:93], v[6:7], v[106:107], v[46:47] op_sel_hi:[0,1,1]
	v_pk_fma_f32 v[70:71], v[66:67], v[4:5], v[54:55] op_sel_hi:[0,1,1]
	v_pk_fma_f32 v[78:79], v[66:67], v[82:83], v[62:63] op_sel_hi:[0,1,1]
	v_pk_fma_f32 v[86:87], v[66:67], v[2:3], v[58:59] op_sel_hi:[0,1,1]
	v_pk_fma_f32 v[96:97], v[66:67], v[106:107], v[50:51] op_sel_hi:[0,1,1]
	v_pk_fma_f32 v[68:69], v[8:9], v[4:5], v[12:13] op_sel_hi:[0,1,1]
	v_pk_fma_f32 v[74:75], v[8:9], v[82:83], v[74:75] op_sel_hi:[0,1,1]
	v_pk_fma_f32 v[84:85], v[8:9], v[2:3], v[76:77] op_sel_hi:[0,1,1]
	v_pk_fma_f32 v[94:95], v[8:9], v[106:107], v[48:49] op_sel_hi:[0,1,1]
	v_pk_fma_f32 v[66:67], v[90:91], v[4:5], v[56:57] op_sel_hi:[0,1,1]
	v_pk_fma_f32 v[76:77], v[90:91], v[82:83], v[64:65] op_sel_hi:[0,1,1]
	v_pk_fma_f32 v[82:83], v[90:91], v[2:3], v[60:61] op_sel_hi:[0,1,1]
	v_pk_fma_f32 v[90:91], v[90:91], v[106:107], v[52:53] op_sel_hi:[0,1,1]
	s_add_i32 s76, s76, 8
	s_andn2_b64 vcc, exec, s[34:35]
	v_mov_b32_e32 v103, v104
	s_waitcnt vmcnt(0)
	v_mov_b64_e32 v[2:3], v[42:43]
	v_mov_b64_e32 v[4:5], v[44:45]
	v_mov_b64_e32 v[6:7], v[38:39]
	v_mov_b64_e32 v[8:9], v[40:41]
	v_mov_b64_e32 v[10:11], v[34:35]
	v_mov_b64_e32 v[12:13], v[36:37]
	v_mov_b64_e32 v[46:47], v[30:31]
	v_mov_b64_e32 v[48:49], v[32:33]
	v_mov_b64_e32 v[50:51], v[26:27]
	v_mov_b64_e32 v[52:53], v[28:29]
	v_mov_b64_e32 v[54:55], v[22:23]
	v_mov_b64_e32 v[56:57], v[24:25]
	v_mov_b64_e32 v[58:59], v[18:19]
	v_mov_b64_e32 v[60:61], v[20:21]
	v_mov_b64_e32 v[62:63], v[14:15]
	v_mov_b64_e32 v[64:65], v[16:17]
	s_cbranch_vccz .LBB0_241
